# v47 with every workgroup running the scan-output sub-phase first and the spatial gating second (no odd/even interleave of the two sub-phases)
# speedup vs baseline: 1.0064x; 1.0045x over previous
; #define LAS __attribute__((address_space(3)))
; DI int opaque_tid() { int t = threadIdx.x; asm volatile("" : "+v"(t)); return t; }
; DI void s3_load(S3Regs& R, const bf16_t* QH, const bf16_t* X, int it, int dir, int ts, int vt, int lane) {
;     int c, h, b; s3_decode(it, c, h, b);
;     const bf16_t* xp = X + ((size_t)((b * 8 + h) * 2 + dir) * 32 + (c >> 1)) * 16384 + (size_t)(32 * vt) * 128 + 8 * lane;
;     const bf16_t* qp = QH + (size_t)dir * ARR + ((size_t)b * SEQ + c * 64 + 32 * ts + (lane >> 4)) * D + h * 128 + 8 * (lane & 15);
; #pragma unroll
;     for (int k = 0; k < 8; ++k) { R.x[k] = *(const u32x4*)(xp + 512 * k); R.q[k] = *(const u32x4*)(qp + (size_t)(4 * k) * D); }
; }
; DI void phase_s3(LAS unsigned char* lds, const bf16_t* QH, const bf16_t* O, const bf16_t* X, const bf16_t* SGA, const float* gw_, bf16_t* YA, int G) {
;     const int tid = opaque_tid(), lane = tid & 63, wave = __builtin_amdgcn_readfirstlane(tid >> 6);
;     const int r = lane & 31, hh = lane >> 5, ts = wave >> 2, vt = wave & 3;
;     LAS bf16_t* XW = (LAS bf16_t*)(lds + wave * 17408);
;     LAS bf16_t* QW = XW + 32 * 136;
;     LAS float* SS0 = (LAS float*)(lds + 8 * 17408);
;     S3Regs R;
;     int it = blockIdx.x;
;     if (it < 2048) s3_load(R, QH, X, it, 0, ts, vt, lane);
; __global__ void __launch_bounds__(512, 2) mega(Args a) {
;     ...
;             if (blk & 1) phase_s3(lds, ZFb, OFb, Xb, SGAb, a.in[4] + l * 128, Hh, G);
.LBB0_122:
	s_and_b64 vcc, exec, s[0:1]
	s_cbranch_vccz .LBB0_148
	v_readlane_b32 s0, v243, 20
	v_readlane_b32 s1, v243, 21
	s_andn2_b64 vcc, exec, s[0:1]
	v_mov_b32_e32 v2, v136
	v_readlane_b32 s6, v243, 22
	v_readlane_b32 s7, v243, 23
	v_readfirstlane_b32 s0, v2
	v_and_b32_e32 v1, 63, v2
	s_ashr_i32 s3, s0, 6
	v_cndmask_b32_e64 v0, 0, 1, s[6:7]
	s_ashr_i32 s2, s0, 8
	s_and_b32 s10, s3, 3
	v_cmp_ne_u32_e64 s[0:1], 1, v0
	s_andn2_b64 vcc, exec, s[6:7]
	v_lshrrev_b32_e32 v0, 4, v1
	s_cbranch_vccnz .LBB0_126
	s_lshl_b32 s6, s10, 13
	v_readlane_b32 s7, v243, 24
	s_add_u32 s6, s7, s6
	v_readlane_b32 s7, v243, 25
	v_readlane_b32 s11, v243, 26
	v_readlane_b32 s14, v242, 24
	s_addc_u32 s7, s7, 0
	s_lshl_b32 s12, s2, 5
	v_or_b32_e32 v3, s11, v0
	v_readlane_b32 s15, v242, 25
	s_ashr_i32 s13, s12, 31
	v_or_b32_e32 v6, s14, v3
	v_mov_b32_e32 v7, s15
	v_lshl_add_u64 v[6:7], v[6:7], 0, s[12:13]
	v_readlane_b32 s12, v243, 27
	v_lshlrev_b32_e32 v48, 4, v1
	v_lshlrev_b64 v[6:7], 11, v[6:7]
	v_readlane_b32 s13, v243, 28
	v_and_b32_e32 v8, 0xf0, v48
	v_mov_b32_e32 v9, v49
	v_lshl_add_u64 v[6:7], s[12:13], 0, v[6:7]
	v_lshl_add_u64 v[6:7], v[6:7], 0, v[8:9]
	s_movk_i32 s11, 0x2000
	v_add_co_u32_e32 v8, vcc, s11, v6
	s_movk_i32 s11, 0x4000
	s_nop 0
	v_addc_co_u32_e32 v9, vcc, 0, v7, vcc
	global_load_dwordx4 v[16:19], v48, s[6:7]
	global_load_dwordx4 v[20:23], v48, s[6:7] offset:1024
	global_load_dwordx4 v[50:53], v[6:7], off
	global_load_dwordx4 v[24:27], v[8:9], off
	v_add_co_u32_e32 v8, vcc, s11, v6
	v_lshl_add_u64 v[4:5], s[6:7], 0, v[48:49]
	s_nop 0
	v_addc_co_u32_e32 v9, vcc, 0, v7, vcc
	global_load_dwordx4 v[28:31], v48, s[6:7] offset:2048
	global_load_dwordx4 v[32:35], v48, s[6:7] offset:3072
	s_movk_i32 s6, 0x6000
	v_add_co_u32_e32 v10, vcc, s6, v6
	s_mov_b32 s6, 0x8000
	s_nop 0
	v_addc_co_u32_e32 v11, vcc, 0, v7, vcc
	v_add_co_u32_e32 v4, vcc, 0x1000, v4
	global_load_dwordx4 v[36:39], v[8:9], off
	global_load_dwordx4 v[40:43], v[10:11], off
	v_addc_co_u32_e32 v5, vcc, 0, v5, vcc
	v_add_co_u32_e32 v8, vcc, s6, v6
	global_load_dwordx4 v[44:47], v[4:5], off
	global_load_dwordx4 v[54:57], v[4:5], off offset:1024
	v_addc_co_u32_e32 v9, vcc, 0, v7, vcc
	v_add_co_u32_e32 v10, vcc, 0xa000, v6
	s_nop 1
	v_addc_co_u32_e32 v11, vcc, 0, v7, vcc
	global_load_dwordx4 v[62:65], v[8:9], off
	global_load_dwordx4 v[66:69], v[10:11], off
	v_add_co_u32_e32 v8, vcc, 0xc000, v6
	global_load_dwordx4 v[58:61], v[4:5], off offset:2048
	global_load_dwordx4 v[70:73], v[4:5], off offset:3072
	v_addc_co_u32_e32 v9, vcc, 0, v7, vcc
	v_add_co_u32_e32 v4, vcc, 0xe000, v6
	s_nop 1
	v_addc_co_u32_e32 v5, vcc, 0, v7, vcc
	global_load_dwordx4 v[74:77], v[8:9], off
	global_load_dwordx4 v[78:81], v[4:5], off

; DI void s3_load(S3Regs& R, const bf16_t* QH, const bf16_t* X, int it, int dir, int ts, int vt, int lane) {
;     int c, h, b; s3_decode(it, c, h, b);
;     const bf16_t* xp = X + ((size_t)((b * 8 + h) * 2 + dir) * 32 + (c >> 1)) * 16384 + (size_t)(32 * vt) * 128 + 8 * lane;
;     const bf16_t* qp = QH + (size_t)dir * ARR + ((size_t)b * SEQ + c * 64 + 32 * ts + (lane >> 4)) * D + h * 128 + 8 * (lane & 15);
; #pragma unroll
;     for (int k = 0; k < 8; ++k) { R.x[k] = *(const u32x4*)(xp + 512 * k); R.q[k] = *(const u32x4*)(qp + (size_t)(4 * k) * D); }
; }
; __global__ void __launch_bounds__(512, 2) mega(Args a) {
;     ...
;             if (blk & 1) phase_s3(lds, ZFb, OFb, Xb, SGAb, a.in[4] + l * 128, Hh, G);
;             __syncthreads();
;             phase_spatial(lds, GVb, UGb, STb, a.in[5] + l * D, a.in[6] + l * D, a.in[7] + (size_t)l * 8 * 128 * 128, a.in[8] + l * 8 * 128, G);
;             __syncthreads();
;             if (!(blk & 1)) phase_s3(lds, ZFb, OFb, Xb, SGAb, a.in[4] + l * 128, Hh, G);
.LBB0_138:
	v_readlane_b32 s0, v243, 18
	v_readlane_b32 s1, v243, 19
	s_andn2_b64 vcc, exec, s[0:1]
	s_barrier
	s_branch .LBB0_148
	v_mov_b32_e32 v2, v136
	v_readlane_b32 s6, v243, 22
	v_readlane_b32 s7, v243, 23
	v_readfirstlane_b32 s0, v2
	v_and_b32_e32 v1, 63, v2
	s_ashr_i32 s3, s0, 6
	v_cndmask_b32_e64 v0, 0, 1, s[6:7]
	s_ashr_i32 s2, s0, 8
	s_and_b32 s10, s3, 3
	v_cmp_ne_u32_e64 s[0:1], 1, v0
	s_andn2_b64 vcc, exec, s[6:7]
	v_lshrrev_b32_e32 v0, 4, v1
	s_cbranch_vccnz .LBB0_141
	s_lshl_b32 s6, s10, 13
	v_readlane_b32 s7, v243, 35
	s_add_u32 s6, s7, s6
	v_readlane_b32 s7, v243, 36
	v_readlane_b32 s11, v243, 37
	v_readlane_b32 s14, v242, 24
	s_addc_u32 s7, s7, 0
	s_lshl_b32 s12, s2, 5
	v_or_b32_e32 v3, s11, v0
	v_readlane_b32 s15, v242, 25
	s_ashr_i32 s13, s12, 31
	v_or_b32_e32 v6, s14, v3
	v_mov_b32_e32 v7, s15
	v_lshl_add_u64 v[6:7], v[6:7], 0, s[12:13]
	v_readlane_b32 s12, v243, 27
	v_lshlrev_b32_e32 v48, 4, v1
	v_lshlrev_b64 v[6:7], 11, v[6:7]
	v_readlane_b32 s13, v243, 28
	v_and_b32_e32 v8, 0xf0, v48
	v_mov_b32_e32 v9, v49
	v_lshl_add_u64 v[6:7], s[12:13], 0, v[6:7]
	v_lshl_add_u64 v[6:7], v[6:7], 0, v[8:9]
	s_movk_i32 s11, 0x2000
	v_add_co_u32_e32 v8, vcc, s11, v6
	s_movk_i32 s11, 0x4000
	s_nop 0
	v_addc_co_u32_e32 v9, vcc, 0, v7, vcc
	global_load_dwordx4 v[16:19], v48, s[6:7]
	global_load_dwordx4 v[20:23], v48, s[6:7] offset:1024
	global_load_dwordx4 v[50:53], v[6:7], off
	global_load_dwordx4 v[24:27], v[8:9], off
	v_add_co_u32_e32 v8, vcc, s11, v6
	v_lshl_add_u64 v[4:5], s[6:7], 0, v[48:49]
	s_nop 0
	v_addc_co_u32_e32 v9, vcc, 0, v7, vcc
	global_load_dwordx4 v[28:31], v48, s[6:7] offset:2048
	global_load_dwordx4 v[32:35], v48, s[6:7] offset:3072
	s_movk_i32 s6, 0x6000
	v_add_co_u32_e32 v10, vcc, s6, v6
	s_mov_b32 s6, 0x8000
	s_nop 0
	v_addc_co_u32_e32 v11, vcc, 0, v7, vcc
	v_add_co_u32_e32 v4, vcc, 0x1000, v4
	global_load_dwordx4 v[36:39], v[8:9], off
	global_load_dwordx4 v[40:43], v[10:11], off
	v_addc_co_u32_e32 v5, vcc, 0, v5, vcc
	v_add_co_u32_e32 v8, vcc, s6, v6
	global_load_dwordx4 v[44:47], v[4:5], off
	global_load_dwordx4 v[54:57], v[4:5], off offset:1024
	v_addc_co_u32_e32 v9, vcc, 0, v7, vcc
	v_add_co_u32_e32 v10, vcc, 0xa000, v6
	s_nop 1
	v_addc_co_u32_e32 v11, vcc, 0, v7, vcc
	global_load_dwordx4 v[62:65], v[8:9], off
	global_load_dwordx4 v[66:69], v[10:11], off
	v_add_co_u32_e32 v8, vcc, 0xc000, v6
	global_load_dwordx4 v[58:61], v[4:5], off offset:2048
	global_load_dwordx4 v[70:73], v[4:5], off offset:3072
	v_addc_co_u32_e32 v9, vcc, 0, v7, vcc
	v_add_co_u32_e32 v4, vcc, 0xe000, v6
	s_nop 1
	v_addc_co_u32_e32 v5, vcc, 0, v7, vcc
	global_load_dwordx4 v[74:77], v[8:9], off
	global_load_dwordx4 v[78:81], v[4:5], off
